# gemm_out: prefetching 256x256 tile loop for 16 panels per XCD group (two even rounds); the 17th panel of the first layer through the original 256x128 tile loop on 8 workgroups
# speedup vs baseline: 1.0081x; 1.0081x over previous
.Lgo_235:
	s_and_b32 s1, 0xffff, s1
	s_and_b64 s[6:7], s[90:91], exec
	s_movk_i32 s6, 0x80
	s_cselect_b32 s6, s6, 0x88
	s_lshr_b32 s1, s6, s1
	s_min_u32 s6, s1, 16
	s_lshl_b32 s6, s6, 2
	s_cmp_ge_i32 s4, s6
	s_cbranch_scc1 .Lgo_end
	v_readlane_b32 s82, v253, 38
	v_readlane_b32 s83, v253, 39
	s_lshl_b32 s80, s74, 21
	s_add_u32 s80, s80, 0xc40000
	s_add_u32 s80, s50, s80
	s_addc_u32 s81, s51, 0
	s_mov_b32 s79, 0
	v_ashrrev_i32_e32 v1, 6, v0
	v_lshrrev_b32_e32 v3, 30, v1
	v_add_u32_e32 v3, v1, v3
	s_mul_i32 s7, s0, s1
	s_lshl_b32 s0, s74, 21
	s_add_u32 s0, s0, 0xc40000
	v_ashrrev_i32_e32 v3, 2, v3
	s_add_u32 s0, s50, s0
	s_waitcnt vmcnt(6)
	v_and_b32_e32 v4, 7, v0
	v_mul_i32_i24_e32 v8, 4, v3
	s_addc_u32 s1, s51, 0
	v_and_b32_e32 v2, 31, v0
	v_lshlrev_b32_e32 v128, 4, v4
	v_sub_u32_e32 v9, v1, v8
	v_lshlrev_b32_e32 v153, 7, v3
	v_ashrrev_i32_e32 v152, 3, v0
	v_bfe_u32 v6, v0, 5, 1
	v_readlane_b32 s8, v253, 38
	v_lshl_add_u64 v[176:177], s[0:1], 0, v[128:129]
	s_movk_i32 s0, 0x90
	v_or_b32_e32 v3, v153, v2
	v_lshl_or_b32 v9, v9, 6, v2
	v_readlane_b32 s9, v253, 39
	v_mul_lo_u32 v7, v152, s0
	v_mul_lo_u32 v3, v3, s0
	v_lshlrev_b32_e32 v10, 4, v6
	v_mul_lo_u32 v9, v9, s0
	v_readlane_b32 s0, v255, 15
	v_readlane_b32 s1, v255, 16
	v_lshl_add_u64 v[250:251], s[8:9], 0, v[128:129]
	v_add3_u32 v154, 0, v3, v10
	v_add_u32_e32 v13, s1, v7
	v_readlane_b32 s8, v255, 17
	v_add3_u32 v155, s0, v3, v10
	v_add_u32_e32 v3, s1, v9
	s_movk_i32 s1, 0x1200
	v_add_u32_e32 v14, s8, v7
	v_readlane_b32 s8, v255, 18
	v_mul_lo_u32 v1, v1, s1
	v_lshlrev_b32_e32 v5, 3, v4
	v_add_u32_e32 v12, s0, v7
	v_add_u32_e32 v15, s8, v7
	v_readlane_b32 s8, v255, 19
	v_add_u32_e32 v1, s0, v1
	v_lshlrev_b32_e32 v2, 1, v2
	v_mul_u32_u24_e32 v6, 0x240, v6
	v_bfe_u32 v157, v0, 3, 3
	s_movk_i32 s0, 0xffc0
	v_add_u32_e32 v4, 0, v128
	v_add_u32_e32 v11, 0, v9
	s_waitcnt vmcnt(3)
	v_add_u32_e32 v16, s8, v7
	v_add_u32_e32 v9, 0, v7
	v_add_u32_e32 v17, v1, v128
	v_add3_u32 v156, v1, v2, v6
	v_mul_u32_u24_e32 v1, 0x90, v157
	v_and_or_b32 v0, v0, s0, v5
	v_lshlrev_b32_e32 v2, 6, v8
	v_mov_b32_e32 v180, 0x2000
	v_or_b32_e32 v171, 8, v157
	v_or_b32_e32 v252, 16, v157
	v_or_b32_e32 v181, 24, v157
	v_sub_u32_e32 v179, v0, v2
	s_lshl_b32 s8, s4, 8
	s_lshl_b32 s9, s5, 8
	v_add_u32_e32 v162, v4, v7
	v_add_u32_e32 v163, v11, v10
	v_add_u32_e32 v164, v12, v128
	v_add_u32_e32 v165, v13, v128
	v_add_u32_e32 v166, v14, v128
	v_add_u32_e32 v167, v15, v128
	v_add_u32_e32 v168, v16, v128
	v_add_u32_e32 v169, v3, v10
	v_add_u32_e32 v128, v9, v128
	v_add_u32_e32 v170, v17, v1
	s_branch .Lgo_239
